# GU GEMM epilogue hand-written (silu*up 8-wide interleaved, bf16 via per-wave LDS transpose, scalar act base + two per-lane offsets), replacing the compiler epilogue
# baseline (speedup 1.0000x reference)
.Lg16_gu_k:
	s_add_i32 s8, s1, 2
	s_lshl_b32 s96, s8, 13
	s_add_i32 m0, vcc_lo, 16384
	v_lshl_add_u64 v[160:161], v[188:189], 0, s[96:97]
	global_load_lds_dwordx4 v[160:161], off
	global_load_lds_dwordx4 v[160:161], off offset:1024
	ds_read_b128 v[196:199], v246 offset:0
	ds_read_b128 v[200:203], v246 offset:1024
	ds_read_b128 v[204:207], v246 offset:2048
	ds_read_b128 v[242:245], v246 offset:3072
	s_add_i32 s8, s1, 2
	s_lshl_b32 s96, s8, 11
	v_lshl_add_u64 v[248:249], v[184:185], 0, s[96:97]
	v_lshl_add_u64 v[250:251], v[186:187], 0, s[96:97]
	s_waitcnt vmcnt(8) lgkmcnt(3)
	v_mfma_f32_16x16x32_bf16 v[112:115], v[128:131], v[196:199], v[112:115]
	v_mfma_f32_16x16x32_bf16 v[120:123], v[132:135], v[196:199], v[120:123]
	v_mfma_f32_16x16x32_bf16 v[80:83], v[136:139], v[196:199], v[80:83]
	v_mfma_f32_16x16x32_bf16 v[88:91], v[140:143], v[196:199], v[88:91]
	ds_read_b128 v[196:199], v246 offset:4096
	s_waitcnt lgkmcnt(3)
	v_mfma_f32_16x16x32_bf16 v[116:119], v[128:131], v[200:203], v[116:119]
	v_mfma_f32_16x16x32_bf16 v[124:127], v[132:135], v[200:203], v[124:127]
	v_mfma_f32_16x16x32_bf16 v[84:87], v[136:139], v[200:203], v[84:87]
	v_mfma_f32_16x16x32_bf16 v[92:95], v[140:143], v[200:203], v[92:95]
	ds_read_b128 v[200:203], v246 offset:5120
	s_waitcnt lgkmcnt(3)
	v_mfma_f32_16x16x32_bf16 v[96:99], v[128:131], v[204:207], v[96:99]
	v_mfma_f32_16x16x32_bf16 v[104:107], v[132:135], v[204:207], v[104:107]
	v_mfma_f32_16x16x32_bf16 v[64:67], v[136:139], v[204:207], v[64:67]
	v_mfma_f32_16x16x32_bf16 v[72:75], v[140:143], v[204:207], v[72:75]
	ds_read_b128 v[204:207], v246 offset:6144
	s_waitcnt lgkmcnt(3)
	v_mfma_f32_16x16x32_bf16 v[100:103], v[128:131], v[242:245], v[100:103]
	v_mfma_f32_16x16x32_bf16 v[108:111], v[132:135], v[242:245], v[108:111]
	v_mfma_f32_16x16x32_bf16 v[68:71], v[136:139], v[242:245], v[68:71]
	v_mfma_f32_16x16x32_bf16 v[76:79], v[140:143], v[242:245], v[76:79]
	ds_read_b128 v[242:245], v246 offset:7168
	s_waitcnt lgkmcnt(3)
	v_mfma_f32_16x16x32_bf16 v[48:51], v[128:131], v[196:199], v[48:51]
	v_mfma_f32_16x16x32_bf16 v[56:59], v[132:135], v[196:199], v[56:59]
	v_mfma_f32_16x16x32_bf16 v[16:19], v[136:139], v[196:199], v[16:19]
	v_mfma_f32_16x16x32_bf16 v[24:27], v[140:143], v[196:199], v[24:27]
	s_waitcnt lgkmcnt(2)
	v_mfma_f32_16x16x32_bf16 v[52:55], v[128:131], v[200:203], v[52:55]
	v_mfma_f32_16x16x32_bf16 v[60:63], v[132:135], v[200:203], v[60:63]
	v_mfma_f32_16x16x32_bf16 v[20:23], v[136:139], v[200:203], v[20:23]
	v_mfma_f32_16x16x32_bf16 v[28:31], v[140:143], v[200:203], v[28:31]
	s_waitcnt lgkmcnt(1)
	v_mfma_f32_16x16x32_bf16 v[32:35], v[128:131], v[204:207], v[32:35]
	v_mfma_f32_16x16x32_bf16 v[40:43], v[132:135], v[204:207], v[40:43]
	v_mfma_f32_16x16x32_bf16 v[0:3], v[136:139], v[204:207], v[0:3]
	v_mfma_f32_16x16x32_bf16 v[8:11], v[140:143], v[204:207], v[8:11]
	s_waitcnt lgkmcnt(0)
	v_mfma_f32_16x16x32_bf16 v[36:39], v[128:131], v[242:245], v[36:39]
	v_mfma_f32_16x16x32_bf16 v[44:47], v[132:135], v[242:245], v[44:47]
	v_mfma_f32_16x16x32_bf16 v[4:7], v[136:139], v[242:245], v[4:7]
	v_mfma_f32_16x16x32_bf16 v[12:15], v[140:143], v[242:245], v[12:15]
	global_load_dwordx4 v[128:131], v[248:249], off
	global_load_dwordx4 v[132:135], v[248:249], off offset:256
	global_load_dwordx4 v[136:139], v[250:251], off
	global_load_dwordx4 v[140:143], v[250:251], off offset:256
	s_waitcnt vmcnt(10)
	s_barrier
	s_add_i32 s8, s1, 3
	s_lshl_b32 s96, s8, 13
	s_mov_b32 m0, vcc_lo
	v_lshl_add_u64 v[160:161], v[188:189], 0, s[96:97]
	global_load_lds_dwordx4 v[160:161], off
	global_load_lds_dwordx4 v[160:161], off offset:1024
	ds_read_b128 v[196:199], v246 offset:8192
	ds_read_b128 v[200:203], v246 offset:9216
	ds_read_b128 v[204:207], v246 offset:10240
	ds_read_b128 v[242:245], v246 offset:11264
	s_add_i32 s8, s1, 3
	s_lshl_b32 s96, s8, 11
	v_lshl_add_u64 v[248:249], v[184:185], 0, s[96:97]
	v_lshl_add_u64 v[250:251], v[186:187], 0, s[96:97]
	s_waitcnt vmcnt(8) lgkmcnt(3)
	v_mfma_f32_16x16x32_bf16 v[112:115], v[144:147], v[196:199], v[112:115]
	v_mfma_f32_16x16x32_bf16 v[120:123], v[148:151], v[196:199], v[120:123]
	v_mfma_f32_16x16x32_bf16 v[80:83], v[152:155], v[196:199], v[80:83]
	v_mfma_f32_16x16x32_bf16 v[88:91], v[156:159], v[196:199], v[88:91]
	ds_read_b128 v[196:199], v246 offset:12288
	s_waitcnt lgkmcnt(3)
	v_mfma_f32_16x16x32_bf16 v[116:119], v[144:147], v[200:203], v[116:119]
	v_mfma_f32_16x16x32_bf16 v[124:127], v[148:151], v[200:203], v[124:127]
	v_mfma_f32_16x16x32_bf16 v[84:87], v[152:155], v[200:203], v[84:87]
	v_mfma_f32_16x16x32_bf16 v[92:95], v[156:159], v[200:203], v[92:95]
	ds_read_b128 v[200:203], v246 offset:13312
	s_waitcnt lgkmcnt(3)
	v_mfma_f32_16x16x32_bf16 v[96:99], v[144:147], v[204:207], v[96:99]
	v_mfma_f32_16x16x32_bf16 v[104:107], v[148:151], v[204:207], v[104:107]
	v_mfma_f32_16x16x32_bf16 v[64:67], v[152:155], v[204:207], v[64:67]
	v_mfma_f32_16x16x32_bf16 v[72:75], v[156:159], v[204:207], v[72:75]
	ds_read_b128 v[204:207], v246 offset:14336
	s_waitcnt lgkmcnt(3)
	v_mfma_f32_16x16x32_bf16 v[100:103], v[144:147], v[242:245], v[100:103]
	v_mfma_f32_16x16x32_bf16 v[108:111], v[148:151], v[242:245], v[108:111]
	v_mfma_f32_16x16x32_bf16 v[68:71], v[152:155], v[242:245], v[68:71]
	v_mfma_f32_16x16x32_bf16 v[76:79], v[156:159], v[242:245], v[76:79]
	ds_read_b128 v[242:245], v246 offset:15360
	s_waitcnt lgkmcnt(3)
	v_mfma_f32_16x16x32_bf16 v[48:51], v[144:147], v[196:199], v[48:51]
	v_mfma_f32_16x16x32_bf16 v[56:59], v[148:151], v[196:199], v[56:59]
	v_mfma_f32_16x16x32_bf16 v[16:19], v[152:155], v[196:199], v[16:19]
	v_mfma_f32_16x16x32_bf16 v[24:27], v[156:159], v[196:199], v[24:27]
	s_waitcnt lgkmcnt(2)
	v_mfma_f32_16x16x32_bf16 v[52:55], v[144:147], v[200:203], v[52:55]
	v_mfma_f32_16x16x32_bf16 v[60:63], v[148:151], v[200:203], v[60:63]
	v_mfma_f32_16x16x32_bf16 v[20:23], v[152:155], v[200:203], v[20:23]
	v_mfma_f32_16x16x32_bf16 v[28:31], v[156:159], v[200:203], v[28:31]
	s_waitcnt lgkmcnt(1)
	v_mfma_f32_16x16x32_bf16 v[32:35], v[144:147], v[204:207], v[32:35]
	v_mfma_f32_16x16x32_bf16 v[40:43], v[148:151], v[204:207], v[40:43]
	v_mfma_f32_16x16x32_bf16 v[0:3], v[152:155], v[204:207], v[0:3]
	v_mfma_f32_16x16x32_bf16 v[8:11], v[156:159], v[204:207], v[8:11]
	s_waitcnt lgkmcnt(0)
	v_mfma_f32_16x16x32_bf16 v[36:39], v[144:147], v[242:245], v[36:39]
	v_mfma_f32_16x16x32_bf16 v[44:47], v[148:151], v[242:245], v[44:47]
	v_mfma_f32_16x16x32_bf16 v[4:7], v[152:155], v[242:245], v[4:7]
	v_mfma_f32_16x16x32_bf16 v[12:15], v[156:159], v[242:245], v[12:15]
	global_load_dwordx4 v[144:147], v[248:249], off
	global_load_dwordx4 v[148:151], v[248:249], off offset:256
	global_load_dwordx4 v[152:155], v[250:251], off
	global_load_dwordx4 v[156:159], v[250:251], off offset:256
	s_waitcnt vmcnt(10)
	s_barrier
	s_add_i32 s8, s1, 4
	s_lshl_b32 s96, s8, 13
	s_add_i32 m0, vcc_lo, 8192
	v_lshl_add_u64 v[160:161], v[188:189], 0, s[96:97]
	global_load_lds_dwordx4 v[160:161], off
	global_load_lds_dwordx4 v[160:161], off offset:1024
	ds_read_b128 v[196:199], v246 offset:16384
	ds_read_b128 v[200:203], v246 offset:17408
	ds_read_b128 v[204:207], v246 offset:18432
	ds_read_b128 v[242:245], v246 offset:19456
	s_add_i32 s8, s1, 4
	s_lshl_b32 s96, s8, 11
	v_lshl_add_u64 v[248:249], v[184:185], 0, s[96:97]
	v_lshl_add_u64 v[250:251], v[186:187], 0, s[96:97]
	s_waitcnt vmcnt(8) lgkmcnt(3)
	v_mfma_f32_16x16x32_bf16 v[112:115], v[128:131], v[196:199], v[112:115]
	v_mfma_f32_16x16x32_bf16 v[120:123], v[132:135], v[196:199], v[120:123]
	v_mfma_f32_16x16x32_bf16 v[80:83], v[136:139], v[196:199], v[80:83]
	v_mfma_f32_16x16x32_bf16 v[88:91], v[140:143], v[196:199], v[88:91]
	ds_read_b128 v[196:199], v246 offset:20480
	s_waitcnt lgkmcnt(3)
	v_mfma_f32_16x16x32_bf16 v[116:119], v[128:131], v[200:203], v[116:119]
	v_mfma_f32_16x16x32_bf16 v[124:127], v[132:135], v[200:203], v[124:127]
	v_mfma_f32_16x16x32_bf16 v[84:87], v[136:139], v[200:203], v[84:87]
	v_mfma_f32_16x16x32_bf16 v[92:95], v[140:143], v[200:203], v[92:95]
	ds_read_b128 v[200:203], v246 offset:21504
	s_waitcnt lgkmcnt(3)
	v_mfma_f32_16x16x32_bf16 v[96:99], v[128:131], v[204:207], v[96:99]
	v_mfma_f32_16x16x32_bf16 v[104:107], v[132:135], v[204:207], v[104:107]
	v_mfma_f32_16x16x32_bf16 v[64:67], v[136:139], v[204:207], v[64:67]
	v_mfma_f32_16x16x32_bf16 v[72:75], v[140:143], v[204:207], v[72:75]
	ds_read_b128 v[204:207], v246 offset:22528
	s_waitcnt lgkmcnt(3)
	v_mfma_f32_16x16x32_bf16 v[100:103], v[128:131], v[242:245], v[100:103]
	v_mfma_f32_16x16x32_bf16 v[108:111], v[132:135], v[242:245], v[108:111]
	v_mfma_f32_16x16x32_bf16 v[68:71], v[136:139], v[242:245], v[68:71]
	v_mfma_f32_16x16x32_bf16 v[76:79], v[140:143], v[242:245], v[76:79]
	ds_read_b128 v[242:245], v246 offset:23552
	s_waitcnt lgkmcnt(3)
	v_mfma_f32_16x16x32_bf16 v[48:51], v[128:131], v[196:199], v[48:51]
	v_mfma_f32_16x16x32_bf16 v[56:59], v[132:135], v[196:199], v[56:59]
	v_mfma_f32_16x16x32_bf16 v[16:19], v[136:139], v[196:199], v[16:19]
	v_mfma_f32_16x16x32_bf16 v[24:27], v[140:143], v[196:199], v[24:27]
	s_waitcnt lgkmcnt(2)
	v_mfma_f32_16x16x32_bf16 v[52:55], v[128:131], v[200:203], v[52:55]
	v_mfma_f32_16x16x32_bf16 v[60:63], v[132:135], v[200:203], v[60:63]
	v_mfma_f32_16x16x32_bf16 v[20:23], v[136:139], v[200:203], v[20:23]
	v_mfma_f32_16x16x32_bf16 v[28:31], v[140:143], v[200:203], v[28:31]
	s_waitcnt lgkmcnt(1)
	v_mfma_f32_16x16x32_bf16 v[32:35], v[128:131], v[204:207], v[32:35]
	v_mfma_f32_16x16x32_bf16 v[40:43], v[132:135], v[204:207], v[40:43]
	v_mfma_f32_16x16x32_bf16 v[0:3], v[136:139], v[204:207], v[0:3]
	v_mfma_f32_16x16x32_bf16 v[8:11], v[140:143], v[204:207], v[8:11]
	s_waitcnt lgkmcnt(0)
	v_mfma_f32_16x16x32_bf16 v[36:39], v[128:131], v[242:245], v[36:39]
	v_mfma_f32_16x16x32_bf16 v[44:47], v[132:135], v[242:245], v[44:47]
	v_mfma_f32_16x16x32_bf16 v[4:7], v[136:139], v[242:245], v[4:7]
	v_mfma_f32_16x16x32_bf16 v[12:15], v[140:143], v[242:245], v[12:15]
	global_load_dwordx4 v[128:131], v[248:249], off
	global_load_dwordx4 v[132:135], v[248:249], off offset:256
	global_load_dwordx4 v[136:139], v[250:251], off
	global_load_dwordx4 v[140:143], v[250:251], off offset:256
	s_waitcnt vmcnt(10)
	s_barrier
	s_add_i32 s8, s1, 5
	s_lshl_b32 s96, s8, 13
	s_add_i32 m0, vcc_lo, 16384
	v_lshl_add_u64 v[160:161], v[188:189], 0, s[96:97]
	global_load_lds_dwordx4 v[160:161], off
	global_load_lds_dwordx4 v[160:161], off offset:1024
	ds_read_b128 v[196:199], v246 offset:0
	ds_read_b128 v[200:203], v246 offset:1024
	ds_read_b128 v[204:207], v246 offset:2048
	ds_read_b128 v[242:245], v246 offset:3072
	s_add_i32 s8, s1, 5
	s_lshl_b32 s96, s8, 11
	v_lshl_add_u64 v[248:249], v[184:185], 0, s[96:97]
	v_lshl_add_u64 v[250:251], v[186:187], 0, s[96:97]
	s_waitcnt vmcnt(8) lgkmcnt(3)
	v_mfma_f32_16x16x32_bf16 v[112:115], v[144:147], v[196:199], v[112:115]
	v_mfma_f32_16x16x32_bf16 v[120:123], v[148:151], v[196:199], v[120:123]
	v_mfma_f32_16x16x32_bf16 v[80:83], v[152:155], v[196:199], v[80:83]
	v_mfma_f32_16x16x32_bf16 v[88:91], v[156:159], v[196:199], v[88:91]
	ds_read_b128 v[196:199], v246 offset:4096
	s_waitcnt lgkmcnt(3)
	v_mfma_f32_16x16x32_bf16 v[116:119], v[144:147], v[200:203], v[116:119]
	v_mfma_f32_16x16x32_bf16 v[124:127], v[148:151], v[200:203], v[124:127]
	v_mfma_f32_16x16x32_bf16 v[84:87], v[152:155], v[200:203], v[84:87]
	v_mfma_f32_16x16x32_bf16 v[92:95], v[156:159], v[200:203], v[92:95]
	ds_read_b128 v[200:203], v246 offset:5120
	s_waitcnt lgkmcnt(3)
	v_mfma_f32_16x16x32_bf16 v[96:99], v[144:147], v[204:207], v[96:99]
	v_mfma_f32_16x16x32_bf16 v[104:107], v[148:151], v[204:207], v[104:107]
	v_mfma_f32_16x16x32_bf16 v[64:67], v[152:155], v[204:207], v[64:67]
	v_mfma_f32_16x16x32_bf16 v[72:75], v[156:159], v[204:207], v[72:75]
	ds_read_b128 v[204:207], v246 offset:6144
	s_waitcnt lgkmcnt(3)
	v_mfma_f32_16x16x32_bf16 v[100:103], v[144:147], v[242:245], v[100:103]
	v_mfma_f32_16x16x32_bf16 v[108:111], v[148:151], v[242:245], v[108:111]
	v_mfma_f32_16x16x32_bf16 v[68:71], v[152:155], v[242:245], v[68:71]
	v_mfma_f32_16x16x32_bf16 v[76:79], v[156:159], v[242:245], v[76:79]
	ds_read_b128 v[242:245], v246 offset:7168
	s_waitcnt lgkmcnt(3)
	v_mfma_f32_16x16x32_bf16 v[48:51], v[144:147], v[196:199], v[48:51]
	v_mfma_f32_16x16x32_bf16 v[56:59], v[148:151], v[196:199], v[56:59]
	v_mfma_f32_16x16x32_bf16 v[16:19], v[152:155], v[196:199], v[16:19]
	v_mfma_f32_16x16x32_bf16 v[24:27], v[156:159], v[196:199], v[24:27]
	s_waitcnt lgkmcnt(2)
	v_mfma_f32_16x16x32_bf16 v[52:55], v[144:147], v[200:203], v[52:55]
	v_mfma_f32_16x16x32_bf16 v[60:63], v[148:151], v[200:203], v[60:63]
	v_mfma_f32_16x16x32_bf16 v[20:23], v[152:155], v[200:203], v[20:23]
	v_mfma_f32_16x16x32_bf16 v[28:31], v[156:159], v[200:203], v[28:31]
	s_waitcnt lgkmcnt(1)
	v_mfma_f32_16x16x32_bf16 v[32:35], v[144:147], v[204:207], v[32:35]
	v_mfma_f32_16x16x32_bf16 v[40:43], v[148:151], v[204:207], v[40:43]
	v_mfma_f32_16x16x32_bf16 v[0:3], v[152:155], v[204:207], v[0:3]
	v_mfma_f32_16x16x32_bf16 v[8:11], v[156:159], v[204:207], v[8:11]
	s_waitcnt lgkmcnt(0)
	v_mfma_f32_16x16x32_bf16 v[36:39], v[144:147], v[242:245], v[36:39]
	v_mfma_f32_16x16x32_bf16 v[44:47], v[148:151], v[242:245], v[44:47]
	v_mfma_f32_16x16x32_bf16 v[4:7], v[152:155], v[242:245], v[4:7]
	v_mfma_f32_16x16x32_bf16 v[12:15], v[156:159], v[242:245], v[12:15]
	global_load_dwordx4 v[144:147], v[248:249], off
	global_load_dwordx4 v[148:151], v[248:249], off offset:256
	global_load_dwordx4 v[152:155], v[250:251], off
	global_load_dwordx4 v[156:159], v[250:251], off offset:256
	s_waitcnt vmcnt(10)
	s_barrier
	s_add_i32 s8, s1, 6
	s_lshl_b32 s96, s8, 13
	s_mov_b32 m0, vcc_lo
	v_lshl_add_u64 v[160:161], v[188:189], 0, s[96:97]
	global_load_lds_dwordx4 v[160:161], off
	global_load_lds_dwordx4 v[160:161], off offset:1024
	ds_read_b128 v[196:199], v246 offset:8192
	ds_read_b128 v[200:203], v246 offset:9216
	ds_read_b128 v[204:207], v246 offset:10240
	ds_read_b128 v[242:245], v246 offset:11264
	s_add_i32 s8, s1, 6
	s_lshl_b32 s96, s8, 11
	v_lshl_add_u64 v[248:249], v[184:185], 0, s[96:97]
	v_lshl_add_u64 v[250:251], v[186:187], 0, s[96:97]
	s_waitcnt vmcnt(8) lgkmcnt(3)
	v_mfma_f32_16x16x32_bf16 v[112:115], v[128:131], v[196:199], v[112:115]
	v_mfma_f32_16x16x32_bf16 v[120:123], v[132:135], v[196:199], v[120:123]
	v_mfma_f32_16x16x32_bf16 v[80:83], v[136:139], v[196:199], v[80:83]
	v_mfma_f32_16x16x32_bf16 v[88:91], v[140:143], v[196:199], v[88:91]
	ds_read_b128 v[196:199], v246 offset:12288
	s_waitcnt lgkmcnt(3)
	v_mfma_f32_16x16x32_bf16 v[116:119], v[128:131], v[200:203], v[116:119]
	v_mfma_f32_16x16x32_bf16 v[124:127], v[132:135], v[200:203], v[124:127]
	v_mfma_f32_16x16x32_bf16 v[84:87], v[136:139], v[200:203], v[84:87]
	v_mfma_f32_16x16x32_bf16 v[92:95], v[140:143], v[200:203], v[92:95]
	ds_read_b128 v[200:203], v246 offset:13312
	s_waitcnt lgkmcnt(3)
	v_mfma_f32_16x16x32_bf16 v[96:99], v[128:131], v[204:207], v[96:99]
	v_mfma_f32_16x16x32_bf16 v[104:107], v[132:135], v[204:207], v[104:107]
	v_mfma_f32_16x16x32_bf16 v[64:67], v[136:139], v[204:207], v[64:67]
	v_mfma_f32_16x16x32_bf16 v[72:75], v[140:143], v[204:207], v[72:75]
	ds_read_b128 v[204:207], v246 offset:14336
	s_waitcnt lgkmcnt(3)
	v_mfma_f32_16x16x32_bf16 v[100:103], v[128:131], v[242:245], v[100:103]
	v_mfma_f32_16x16x32_bf16 v[108:111], v[132:135], v[242:245], v[108:111]
	v_mfma_f32_16x16x32_bf16 v[68:71], v[136:139], v[242:245], v[68:71]
	v_mfma_f32_16x16x32_bf16 v[76:79], v[140:143], v[242:245], v[76:79]
	ds_read_b128 v[242:245], v246 offset:15360
	s_waitcnt lgkmcnt(3)
	v_mfma_f32_16x16x32_bf16 v[48:51], v[128:131], v[196:199], v[48:51]
	v_mfma_f32_16x16x32_bf16 v[56:59], v[132:135], v[196:199], v[56:59]
	v_mfma_f32_16x16x32_bf16 v[16:19], v[136:139], v[196:199], v[16:19]
	v_mfma_f32_16x16x32_bf16 v[24:27], v[140:143], v[196:199], v[24:27]
	s_waitcnt lgkmcnt(2)
	v_mfma_f32_16x16x32_bf16 v[52:55], v[128:131], v[200:203], v[52:55]
	v_mfma_f32_16x16x32_bf16 v[60:63], v[132:135], v[200:203], v[60:63]
	v_mfma_f32_16x16x32_bf16 v[20:23], v[136:139], v[200:203], v[20:23]
	v_mfma_f32_16x16x32_bf16 v[28:31], v[140:143], v[200:203], v[28:31]
	s_waitcnt lgkmcnt(1)
	v_mfma_f32_16x16x32_bf16 v[32:35], v[128:131], v[204:207], v[32:35]
	v_mfma_f32_16x16x32_bf16 v[40:43], v[132:135], v[204:207], v[40:43]
	v_mfma_f32_16x16x32_bf16 v[0:3], v[136:139], v[204:207], v[0:3]
	v_mfma_f32_16x16x32_bf16 v[8:11], v[140:143], v[204:207], v[8:11]
	s_waitcnt lgkmcnt(0)
	v_mfma_f32_16x16x32_bf16 v[36:39], v[128:131], v[242:245], v[36:39]
	v_mfma_f32_16x16x32_bf16 v[44:47], v[132:135], v[242:245], v[44:47]
	v_mfma_f32_16x16x32_bf16 v[4:7], v[136:139], v[242:245], v[4:7]
	v_mfma_f32_16x16x32_bf16 v[12:15], v[140:143], v[242:245], v[12:15]
	global_load_dwordx4 v[128:131], v[248:249], off
	global_load_dwordx4 v[132:135], v[248:249], off offset:256
	global_load_dwordx4 v[136:139], v[250:251], off
	global_load_dwordx4 v[140:143], v[250:251], off offset:256
	s_waitcnt vmcnt(10)
	s_barrier
	s_add_i32 s8, s1, 7
	s_lshl_b32 s96, s8, 13
	s_add_i32 m0, vcc_lo, 8192
	v_lshl_add_u64 v[160:161], v[188:189], 0, s[96:97]
	global_load_lds_dwordx4 v[160:161], off
	global_load_lds_dwordx4 v[160:161], off offset:1024
	ds_read_b128 v[196:199], v246 offset:16384
	ds_read_b128 v[200:203], v246 offset:17408
	ds_read_b128 v[204:207], v246 offset:18432
	ds_read_b128 v[242:245], v246 offset:19456
	s_add_i32 s8, s1, 7
	s_lshl_b32 s96, s8, 11
	v_lshl_add_u64 v[248:249], v[184:185], 0, s[96:97]
	v_lshl_add_u64 v[250:251], v[186:187], 0, s[96:97]
	s_waitcnt vmcnt(8) lgkmcnt(3)
	v_mfma_f32_16x16x32_bf16 v[112:115], v[144:147], v[196:199], v[112:115]
	v_mfma_f32_16x16x32_bf16 v[120:123], v[148:151], v[196:199], v[120:123]
	v_mfma_f32_16x16x32_bf16 v[80:83], v[152:155], v[196:199], v[80:83]
	v_mfma_f32_16x16x32_bf16 v[88:91], v[156:159], v[196:199], v[88:91]
	ds_read_b128 v[196:199], v246 offset:20480
	s_waitcnt lgkmcnt(3)
	v_mfma_f32_16x16x32_bf16 v[116:119], v[144:147], v[200:203], v[116:119]
	v_mfma_f32_16x16x32_bf16 v[124:127], v[148:151], v[200:203], v[124:127]
	v_mfma_f32_16x16x32_bf16 v[84:87], v[152:155], v[200:203], v[84:87]
	v_mfma_f32_16x16x32_bf16 v[92:95], v[156:159], v[200:203], v[92:95]
	ds_read_b128 v[200:203], v246 offset:21504
	s_waitcnt lgkmcnt(3)
	v_mfma_f32_16x16x32_bf16 v[96:99], v[144:147], v[204:207], v[96:99]
	v_mfma_f32_16x16x32_bf16 v[104:107], v[148:151], v[204:207], v[104:107]
	v_mfma_f32_16x16x32_bf16 v[64:67], v[152:155], v[204:207], v[64:67]
	v_mfma_f32_16x16x32_bf16 v[72:75], v[156:159], v[204:207], v[72:75]
	ds_read_b128 v[204:207], v246 offset:22528
	s_waitcnt lgkmcnt(3)
	v_mfma_f32_16x16x32_bf16 v[100:103], v[144:147], v[242:245], v[100:103]
	v_mfma_f32_16x16x32_bf16 v[108:111], v[148:151], v[242:245], v[108:111]
	v_mfma_f32_16x16x32_bf16 v[68:71], v[152:155], v[242:245], v[68:71]
	v_mfma_f32_16x16x32_bf16 v[76:79], v[156:159], v[242:245], v[76:79]
	ds_read_b128 v[242:245], v246 offset:23552
	s_waitcnt lgkmcnt(3)
	v_mfma_f32_16x16x32_bf16 v[48:51], v[144:147], v[196:199], v[48:51]
	v_mfma_f32_16x16x32_bf16 v[56:59], v[148:151], v[196:199], v[56:59]
	v_mfma_f32_16x16x32_bf16 v[16:19], v[152:155], v[196:199], v[16:19]
	v_mfma_f32_16x16x32_bf16 v[24:27], v[156:159], v[196:199], v[24:27]
	s_waitcnt lgkmcnt(2)
	v_mfma_f32_16x16x32_bf16 v[52:55], v[144:147], v[200:203], v[52:55]
	v_mfma_f32_16x16x32_bf16 v[60:63], v[148:151], v[200:203], v[60:63]
	v_mfma_f32_16x16x32_bf16 v[20:23], v[152:155], v[200:203], v[20:23]
	v_mfma_f32_16x16x32_bf16 v[28:31], v[156:159], v[200:203], v[28:31]
	s_waitcnt lgkmcnt(1)
	v_mfma_f32_16x16x32_bf16 v[32:35], v[144:147], v[204:207], v[32:35]
	v_mfma_f32_16x16x32_bf16 v[40:43], v[148:151], v[204:207], v[40:43]
	v_mfma_f32_16x16x32_bf16 v[0:3], v[152:155], v[204:207], v[0:3]
	v_mfma_f32_16x16x32_bf16 v[8:11], v[156:159], v[204:207], v[8:11]
	s_waitcnt lgkmcnt(0)
	v_mfma_f32_16x16x32_bf16 v[36:39], v[144:147], v[242:245], v[36:39]
	v_mfma_f32_16x16x32_bf16 v[44:47], v[148:151], v[242:245], v[44:47]
	v_mfma_f32_16x16x32_bf16 v[4:7], v[152:155], v[242:245], v[4:7]
	v_mfma_f32_16x16x32_bf16 v[12:15], v[156:159], v[242:245], v[12:15]
	global_load_dwordx4 v[144:147], v[248:249], off
	global_load_dwordx4 v[148:151], v[248:249], off offset:256
	global_load_dwordx4 v[152:155], v[250:251], off
	global_load_dwordx4 v[156:159], v[250:251], off offset:256
	s_waitcnt vmcnt(10)
	s_barrier
	s_add_i32 s1, s1, 6
	s_cmp_lt_u32 s1, 30
	s_cbranch_scc1 .Lg16_gu_k
	ds_read_b128 v[196:199], v246 offset:0
	ds_read_b128 v[200:203], v246 offset:1024
	ds_read_b128 v[204:207], v246 offset:2048
	ds_read_b128 v[242:245], v246 offset:3072
	s_waitcnt vmcnt(6) lgkmcnt(3)
	v_mfma_f32_16x16x32_bf16 v[112:115], v[128:131], v[196:199], v[112:115]
	v_mfma_f32_16x16x32_bf16 v[120:123], v[132:135], v[196:199], v[120:123]
	v_mfma_f32_16x16x32_bf16 v[80:83], v[136:139], v[196:199], v[80:83]
	v_mfma_f32_16x16x32_bf16 v[88:91], v[140:143], v[196:199], v[88:91]
	ds_read_b128 v[196:199], v246 offset:4096
	s_waitcnt lgkmcnt(3)
	v_mfma_f32_16x16x32_bf16 v[116:119], v[128:131], v[200:203], v[116:119]
	v_mfma_f32_16x16x32_bf16 v[124:127], v[132:135], v[200:203], v[124:127]
	v_mfma_f32_16x16x32_bf16 v[84:87], v[136:139], v[200:203], v[84:87]
	v_mfma_f32_16x16x32_bf16 v[92:95], v[140:143], v[200:203], v[92:95]
	ds_read_b128 v[200:203], v246 offset:5120
	s_waitcnt lgkmcnt(3)
	v_mfma_f32_16x16x32_bf16 v[96:99], v[128:131], v[204:207], v[96:99]
	v_mfma_f32_16x16x32_bf16 v[104:107], v[132:135], v[204:207], v[104:107]
	v_mfma_f32_16x16x32_bf16 v[64:67], v[136:139], v[204:207], v[64:67]
	v_mfma_f32_16x16x32_bf16 v[72:75], v[140:143], v[204:207], v[72:75]
	ds_read_b128 v[204:207], v246 offset:6144
	s_waitcnt lgkmcnt(3)
	v_mfma_f32_16x16x32_bf16 v[100:103], v[128:131], v[242:245], v[100:103]
	v_mfma_f32_16x16x32_bf16 v[108:111], v[132:135], v[242:245], v[108:111]
	v_mfma_f32_16x16x32_bf16 v[68:71], v[136:139], v[242:245], v[68:71]
	v_mfma_f32_16x16x32_bf16 v[76:79], v[140:143], v[242:245], v[76:79]
	ds_read_b128 v[242:245], v246 offset:7168
	s_waitcnt lgkmcnt(3)
	v_mfma_f32_16x16x32_bf16 v[48:51], v[128:131], v[196:199], v[48:51]
	v_mfma_f32_16x16x32_bf16 v[56:59], v[132:135], v[196:199], v[56:59]
	v_mfma_f32_16x16x32_bf16 v[16:19], v[136:139], v[196:199], v[16:19]
	v_mfma_f32_16x16x32_bf16 v[24:27], v[140:143], v[196:199], v[24:27]
	s_waitcnt lgkmcnt(2)
	v_mfma_f32_16x16x32_bf16 v[52:55], v[128:131], v[200:203], v[52:55]
	v_mfma_f32_16x16x32_bf16 v[60:63], v[132:135], v[200:203], v[60:63]
	v_mfma_f32_16x16x32_bf16 v[20:23], v[136:139], v[200:203], v[20:23]
	v_mfma_f32_16x16x32_bf16 v[28:31], v[140:143], v[200:203], v[28:31]
	s_waitcnt lgkmcnt(1)
	v_mfma_f32_16x16x32_bf16 v[32:35], v[128:131], v[204:207], v[32:35]
	v_mfma_f32_16x16x32_bf16 v[40:43], v[132:135], v[204:207], v[40:43]
	v_mfma_f32_16x16x32_bf16 v[0:3], v[136:139], v[204:207], v[0:3]
	v_mfma_f32_16x16x32_bf16 v[8:11], v[140:143], v[204:207], v[8:11]
	s_waitcnt lgkmcnt(0)
	v_mfma_f32_16x16x32_bf16 v[36:39], v[128:131], v[242:245], v[36:39]
	v_mfma_f32_16x16x32_bf16 v[44:47], v[132:135], v[242:245], v[44:47]
	v_mfma_f32_16x16x32_bf16 v[4:7], v[136:139], v[242:245], v[4:7]
	v_mfma_f32_16x16x32_bf16 v[12:15], v[140:143], v[242:245], v[12:15]
	s_waitcnt vmcnt(4)
	s_barrier
	ds_read_b128 v[196:199], v246 offset:8192
	ds_read_b128 v[200:203], v246 offset:9216
	ds_read_b128 v[204:207], v246 offset:10240
	ds_read_b128 v[242:245], v246 offset:11264
	s_waitcnt vmcnt(0) lgkmcnt(3)
	v_mfma_f32_16x16x32_bf16 v[112:115], v[144:147], v[196:199], v[112:115]
	v_mfma_f32_16x16x32_bf16 v[120:123], v[148:151], v[196:199], v[120:123]
	v_mfma_f32_16x16x32_bf16 v[80:83], v[152:155], v[196:199], v[80:83]
	v_mfma_f32_16x16x32_bf16 v[88:91], v[156:159], v[196:199], v[88:91]
	ds_read_b128 v[196:199], v246 offset:12288
	s_waitcnt lgkmcnt(3)
	v_mfma_f32_16x16x32_bf16 v[116:119], v[144:147], v[200:203], v[116:119]
	v_mfma_f32_16x16x32_bf16 v[124:127], v[148:151], v[200:203], v[124:127]
	v_mfma_f32_16x16x32_bf16 v[84:87], v[152:155], v[200:203], v[84:87]
	v_mfma_f32_16x16x32_bf16 v[92:95], v[156:159], v[200:203], v[92:95]
	ds_read_b128 v[200:203], v246 offset:13312
	s_waitcnt lgkmcnt(3)
	v_mfma_f32_16x16x32_bf16 v[96:99], v[144:147], v[204:207], v[96:99]
	v_mfma_f32_16x16x32_bf16 v[104:107], v[148:151], v[204:207], v[104:107]
	v_mfma_f32_16x16x32_bf16 v[64:67], v[152:155], v[204:207], v[64:67]
	v_mfma_f32_16x16x32_bf16 v[72:75], v[156:159], v[204:207], v[72:75]
	ds_read_b128 v[204:207], v246 offset:14336
	s_waitcnt lgkmcnt(3)
	v_mfma_f32_16x16x32_bf16 v[100:103], v[144:147], v[242:245], v[100:103]
	v_mfma_f32_16x16x32_bf16 v[108:111], v[148:151], v[242:245], v[108:111]
	v_mfma_f32_16x16x32_bf16 v[68:71], v[152:155], v[242:245], v[68:71]
	v_mfma_f32_16x16x32_bf16 v[76:79], v[156:159], v[242:245], v[76:79]
	ds_read_b128 v[242:245], v246 offset:15360
	v_permlane16_swap_b32_e32 v112, v116
	v_permlane16_swap_b32_e32 v113, v117
	v_permlane16_swap_b32_e32 v114, v118
	v_permlane16_swap_b32_e32 v115, v119
	v_permlane16_swap_b32_e32 v120, v124
	v_permlane16_swap_b32_e32 v121, v125
	v_permlane16_swap_b32_e32 v122, v126
	v_permlane16_swap_b32_e32 v123, v127
	v_permlane16_swap_b32_e32 v80, v84
	v_permlane16_swap_b32_e32 v81, v85
	v_permlane16_swap_b32_e32 v82, v86
	v_permlane16_swap_b32_e32 v83, v87
	v_permlane16_swap_b32_e32 v88, v92
	v_permlane16_swap_b32_e32 v89, v93
	v_permlane16_swap_b32_e32 v90, v94
	v_permlane16_swap_b32_e32 v91, v95
	v_permlane32_swap_b32_e32 v112, v116
	v_permlane32_swap_b32_e32 v113, v117
	v_permlane32_swap_b32_e32 v114, v118
	v_permlane32_swap_b32_e32 v115, v119
	v_permlane32_swap_b32_e32 v120, v124
	v_permlane32_swap_b32_e32 v121, v125
	v_permlane32_swap_b32_e32 v122, v126
	v_permlane32_swap_b32_e32 v123, v127
	v_permlane32_swap_b32_e32 v80, v84
	v_permlane32_swap_b32_e32 v81, v85
	v_permlane32_swap_b32_e32 v82, v86
	v_permlane32_swap_b32_e32 v83, v87
	v_permlane32_swap_b32_e32 v88, v92
	v_permlane32_swap_b32_e32 v89, v93
	v_permlane32_swap_b32_e32 v90, v94
	v_permlane32_swap_b32_e32 v91, v95
	s_waitcnt lgkmcnt(3)
	v_mfma_f32_16x16x32_bf16 v[48:51], v[144:147], v[196:199], v[48:51]
	v_mfma_f32_16x16x32_bf16 v[56:59], v[148:151], v[196:199], v[56:59]
	v_mfma_f32_16x16x32_bf16 v[16:19], v[152:155], v[196:199], v[16:19]
	v_mfma_f32_16x16x32_bf16 v[24:27], v[156:159], v[196:199], v[24:27]
	s_waitcnt lgkmcnt(2)
	v_mfma_f32_16x16x32_bf16 v[52:55], v[144:147], v[200:203], v[52:55]
	v_mfma_f32_16x16x32_bf16 v[60:63], v[148:151], v[200:203], v[60:63]
	v_mfma_f32_16x16x32_bf16 v[20:23], v[152:155], v[200:203], v[20:23]
	v_mfma_f32_16x16x32_bf16 v[28:31], v[156:159], v[200:203], v[28:31]
	v_permlane16_swap_b32_e32 v96, v100
	v_permlane16_swap_b32_e32 v97, v101
	v_permlane16_swap_b32_e32 v98, v102
	v_permlane16_swap_b32_e32 v99, v103
	v_permlane16_swap_b32_e32 v104, v108
	v_permlane16_swap_b32_e32 v105, v109
	v_permlane16_swap_b32_e32 v106, v110
	v_permlane16_swap_b32_e32 v107, v111
	v_permlane16_swap_b32_e32 v64, v68
	v_permlane16_swap_b32_e32 v65, v69
	v_permlane16_swap_b32_e32 v66, v70
	v_permlane16_swap_b32_e32 v67, v71
	v_permlane16_swap_b32_e32 v72, v76
	v_permlane16_swap_b32_e32 v73, v77
	v_permlane16_swap_b32_e32 v74, v78
	v_permlane16_swap_b32_e32 v75, v79
	v_permlane32_swap_b32_e32 v96, v100
	v_permlane32_swap_b32_e32 v97, v101
	v_permlane32_swap_b32_e32 v98, v102
	v_permlane32_swap_b32_e32 v99, v103
	v_permlane32_swap_b32_e32 v104, v108
	v_permlane32_swap_b32_e32 v105, v109
	v_permlane32_swap_b32_e32 v106, v110
	v_permlane32_swap_b32_e32 v107, v111
	v_permlane32_swap_b32_e32 v64, v68
	v_permlane32_swap_b32_e32 v65, v69
	v_permlane32_swap_b32_e32 v66, v70
	v_permlane32_swap_b32_e32 v67, v71
	v_permlane32_swap_b32_e32 v72, v76
	v_permlane32_swap_b32_e32 v73, v77
	v_permlane32_swap_b32_e32 v74, v78
	v_permlane32_swap_b32_e32 v75, v79
	s_waitcnt lgkmcnt(1)
	v_mfma_f32_16x16x32_bf16 v[32:35], v[144:147], v[204:207], v[32:35]
	v_mfma_f32_16x16x32_bf16 v[40:43], v[148:151], v[204:207], v[40:43]
	v_mfma_f32_16x16x32_bf16 v[0:3], v[152:155], v[204:207], v[0:3]
	v_mfma_f32_16x16x32_bf16 v[8:11], v[156:159], v[204:207], v[8:11]
	s_waitcnt lgkmcnt(0)
	v_mfma_f32_16x16x32_bf16 v[36:39], v[144:147], v[242:245], v[36:39]
	v_mfma_f32_16x16x32_bf16 v[44:47], v[148:151], v[242:245], v[44:47]
	v_mfma_f32_16x16x32_bf16 v[4:7], v[152:155], v[242:245], v[4:7]
	v_mfma_f32_16x16x32_bf16 v[12:15], v[156:159], v[242:245], v[12:15]
	v_permlane16_swap_b32_e32 v48, v52
	v_permlane16_swap_b32_e32 v49, v53
	v_permlane16_swap_b32_e32 v50, v54
	v_permlane16_swap_b32_e32 v51, v55
	v_permlane16_swap_b32_e32 v56, v60
	v_permlane16_swap_b32_e32 v57, v61
	v_permlane16_swap_b32_e32 v58, v62
	v_permlane16_swap_b32_e32 v59, v63
	v_permlane16_swap_b32_e32 v16, v20
	v_permlane16_swap_b32_e32 v17, v21
	v_permlane16_swap_b32_e32 v18, v22
	v_permlane16_swap_b32_e32 v19, v23
	v_permlane16_swap_b32_e32 v24, v28
	v_permlane16_swap_b32_e32 v25, v29
	v_permlane16_swap_b32_e32 v26, v30
	v_permlane16_swap_b32_e32 v27, v31
	v_permlane32_swap_b32_e32 v48, v52
	v_permlane32_swap_b32_e32 v49, v53
	v_permlane32_swap_b32_e32 v50, v54
	v_permlane32_swap_b32_e32 v51, v55
	v_permlane32_swap_b32_e32 v56, v60
	v_permlane32_swap_b32_e32 v57, v61
	v_permlane32_swap_b32_e32 v58, v62
	v_permlane32_swap_b32_e32 v59, v63
	v_permlane32_swap_b32_e32 v16, v20
	v_permlane32_swap_b32_e32 v17, v21
	v_permlane32_swap_b32_e32 v18, v22
	v_permlane32_swap_b32_e32 v19, v23
	v_permlane32_swap_b32_e32 v24, v28
	v_permlane32_swap_b32_e32 v25, v29
	v_permlane32_swap_b32_e32 v26, v30
	v_permlane32_swap_b32_e32 v27, v31
	s_barrier
	s_nop 7
	v_permlane16_swap_b32_e32 v32, v36
	v_permlane16_swap_b32_e32 v33, v37
	v_permlane16_swap_b32_e32 v34, v38
	v_permlane16_swap_b32_e32 v35, v39
	v_permlane16_swap_b32_e32 v40, v44
	v_permlane16_swap_b32_e32 v41, v45
	v_permlane16_swap_b32_e32 v42, v46
	v_permlane16_swap_b32_e32 v43, v47
	v_permlane16_swap_b32_e32 v0, v4
	v_permlane16_swap_b32_e32 v1, v5
	v_permlane16_swap_b32_e32 v2, v6
	v_permlane16_swap_b32_e32 v3, v7
	v_permlane16_swap_b32_e32 v8, v12
	v_permlane16_swap_b32_e32 v9, v13
	v_permlane16_swap_b32_e32 v10, v14
	v_permlane16_swap_b32_e32 v11, v15
	v_permlane32_swap_b32_e32 v32, v36
	v_permlane32_swap_b32_e32 v33, v37
	v_permlane32_swap_b32_e32 v34, v38
	v_permlane32_swap_b32_e32 v35, v39
	v_permlane32_swap_b32_e32 v40, v44
	v_permlane32_swap_b32_e32 v41, v45
	v_permlane32_swap_b32_e32 v42, v46
	v_permlane32_swap_b32_e32 v43, v47
	v_permlane32_swap_b32_e32 v0, v4
	v_permlane32_swap_b32_e32 v1, v5
	v_permlane32_swap_b32_e32 v2, v6
	v_permlane32_swap_b32_e32 v3, v7
	v_permlane32_swap_b32_e32 v8, v12
	v_permlane32_swap_b32_e32 v9, v13
	v_permlane32_swap_b32_e32 v10, v14
	v_permlane32_swap_b32_e32 v11, v15
	s_waitcnt vmcnt(0)
	s_waitcnt vmcnt(0)
	v_and_b32_e32 v128, 63, v179
	v_lshrrev_b32_e32 v129, 6, v179
	s_lshl_b32 s14, s7, 3
	s_mul_hi_u32 s15, s14, 0x2c000
	s_mul_i32 s14, s14, 0x2c000
	s_lshl_b32 s16, s0, 12
	s_add_u32 s12, s66, s14
	s_addc_u32 s13, s67, s15
	s_add_u32 s12, s12, s16
	s_addc_u32 s13, s13, 0
	v_mul_u32_u24_e32 v188, 0x2400, v129
	v_lshrrev_b32_e32 v189, 5, v128
	v_mul_u32_u24_e32 v189, 0x240, v189
	v_add_u32_e32 v130, v188, v189
	v_and_b32_e32 v189, 31, v128
	v_lshl_add_u32 v130, v189, 1, v130
	v_lshrrev_b32_e32 v189, 2, v128
	v_mul_u32_u24_e32 v131, 0x90, v189
	v_add_u32_e32 v131, v131, v188
	v_and_b32_e32 v188, 3, v128
	v_lshl_add_u32 v131, v188, 4, v131
	v_lshlrev_b32_e32 v132, 4, v189
	v_and_b32_e32 v189, 1, v188
	v_lshl_add_u32 v132, v189, 9, v132
	v_lshrrev_b32_e32 v189, 1, v188
	v_lshl_add_u32 v132, v189, 10, v132
	v_mul_u32_u24_e32 v189, 0x58000, v129
	v_add_u32_e32 v132, v132, v189
	v_add_u32_e32 v133, 0x2c000, v132
	v_mul_f32_e32 v140, 0xbfb8aa3b, v112
	v_mul_f32_e32 v141, 0xbfb8aa3b, v113
	v_mul_f32_e32 v142, 0xbfb8aa3b, v114
	v_mul_f32_e32 v143, 0xbfb8aa3b, v115
	v_mul_f32_e32 v144, 0xbfb8aa3b, v116
	v_mul_f32_e32 v145, 0xbfb8aa3b, v117
	v_mul_f32_e32 v146, 0xbfb8aa3b, v118
	v_mul_f32_e32 v147, 0xbfb8aa3b, v119
	v_exp_f32_e32 v140, v140
	v_exp_f32_e32 v141, v141
	v_exp_f32_e32 v142, v142
	v_exp_f32_e32 v143, v143
	v_exp_f32_e32 v144, v144
	v_exp_f32_e32 v145, v145
	v_exp_f32_e32 v146, v146
	v_exp_f32_e32 v147, v147
	v_add_f32_e32 v140, 1.0, v140
	v_add_f32_e32 v141, 1.0, v141
	v_add_f32_e32 v142, 1.0, v142
	v_add_f32_e32 v143, 1.0, v143
	v_add_f32_e32 v144, 1.0, v144
	v_add_f32_e32 v145, 1.0, v145
	v_add_f32_e32 v146, 1.0, v146
	v_add_f32_e32 v147, 1.0, v147
	v_rcp_f32_e32 v140, v140
	v_rcp_f32_e32 v141, v141
	v_rcp_f32_e32 v142, v142
	v_rcp_f32_e32 v143, v143
	v_rcp_f32_e32 v144, v144
	v_rcp_f32_e32 v145, v145
	v_rcp_f32_e32 v146, v146
	v_rcp_f32_e32 v147, v147
	v_mul_f32_e32 v140, v112, v140
	v_mul_f32_e32 v141, v113, v141
	v_mul_f32_e32 v142, v114, v142
	v_mul_f32_e32 v143, v115, v143
	v_mul_f32_e32 v144, v116, v144
	v_mul_f32_e32 v145, v117, v145
	v_mul_f32_e32 v146, v118, v146
	v_mul_f32_e32 v147, v119, v147
	v_mul_f32_e32 v140, v96, v140
	v_mul_f32_e32 v141, v97, v141
	v_mul_f32_e32 v142, v98, v142
	v_mul_f32_e32 v143, v99, v143
	v_mul_f32_e32 v144, v100, v144
	v_mul_f32_e32 v145, v101, v145
	v_mul_f32_e32 v146, v102, v146
	v_mul_f32_e32 v147, v103, v147
	v_cvt_pk_bf16_f32 v140, v140, v140
	v_cvt_pk_bf16_f32 v141, v141, v141
	v_cvt_pk_bf16_f32 v142, v142, v142
	v_cvt_pk_bf16_f32 v143, v143, v143
	v_cvt_pk_bf16_f32 v144, v144, v144
	v_cvt_pk_bf16_f32 v145, v145, v145
	v_cvt_pk_bf16_f32 v146, v146, v146
	v_cvt_pk_bf16_f32 v147, v147, v147
	ds_write_b16 v130, v140
	ds_write_b16 v130, v141 offset:144
	ds_write_b16 v130, v142 offset:288
	ds_write_b16 v130, v143 offset:432
	ds_write_b16 v130, v144 offset:1152
	ds_write_b16 v130, v145 offset:1296
	ds_write_b16 v130, v146 offset:1440
	ds_write_b16 v130, v147 offset:1584
	v_mul_f32_e32 v140, 0xbfb8aa3b, v120
	v_mul_f32_e32 v141, 0xbfb8aa3b, v121
	v_mul_f32_e32 v142, 0xbfb8aa3b, v122
	v_mul_f32_e32 v143, 0xbfb8aa3b, v123
	v_mul_f32_e32 v144, 0xbfb8aa3b, v124
	v_mul_f32_e32 v145, 0xbfb8aa3b, v125
	v_mul_f32_e32 v146, 0xbfb8aa3b, v126
	v_mul_f32_e32 v147, 0xbfb8aa3b, v127
	v_exp_f32_e32 v140, v140
	v_exp_f32_e32 v141, v141
	v_exp_f32_e32 v142, v142
	v_exp_f32_e32 v143, v143
	v_exp_f32_e32 v144, v144
	v_exp_f32_e32 v145, v145
	v_exp_f32_e32 v146, v146
	v_exp_f32_e32 v147, v147
	v_add_f32_e32 v140, 1.0, v140
	v_add_f32_e32 v141, 1.0, v141
	v_add_f32_e32 v142, 1.0, v142
	v_add_f32_e32 v143, 1.0, v143
	v_add_f32_e32 v144, 1.0, v144
	v_add_f32_e32 v145, 1.0, v145
	v_add_f32_e32 v146, 1.0, v146
	v_add_f32_e32 v147, 1.0, v147
	v_rcp_f32_e32 v140, v140
	v_rcp_f32_e32 v141, v141
	v_rcp_f32_e32 v142, v142
	v_rcp_f32_e32 v143, v143
	v_rcp_f32_e32 v144, v144
	v_rcp_f32_e32 v145, v145
	v_rcp_f32_e32 v146, v146
	v_rcp_f32_e32 v147, v147
	v_mul_f32_e32 v140, v120, v140
	v_mul_f32_e32 v141, v121, v141
	v_mul_f32_e32 v142, v122, v142
	v_mul_f32_e32 v143, v123, v143
	v_mul_f32_e32 v144, v124, v144
	v_mul_f32_e32 v145, v125, v145
	v_mul_f32_e32 v146, v126, v146
	v_mul_f32_e32 v147, v127, v147
	v_mul_f32_e32 v140, v104, v140
	v_mul_f32_e32 v141, v105, v141
	v_mul_f32_e32 v142, v106, v142
	v_mul_f32_e32 v143, v107, v143
	v_mul_f32_e32 v144, v108, v144
	v_mul_f32_e32 v145, v109, v145
	v_mul_f32_e32 v146, v110, v146
	v_mul_f32_e32 v147, v111, v147
	v_cvt_pk_bf16_f32 v140, v140, v140
	v_cvt_pk_bf16_f32 v141, v141, v141
	v_cvt_pk_bf16_f32 v142, v142, v142
	v_cvt_pk_bf16_f32 v143, v143, v143
	v_cvt_pk_bf16_f32 v144, v144, v144
	v_cvt_pk_bf16_f32 v145, v145, v145
	v_cvt_pk_bf16_f32 v146, v146, v146
	v_cvt_pk_bf16_f32 v147, v147, v147
	ds_write_b16 v130, v140 offset:2304
	ds_write_b16 v130, v141 offset:2448
	ds_write_b16 v130, v142 offset:2592
	ds_write_b16 v130, v143 offset:2736
	ds_write_b16 v130, v144 offset:3456
	ds_write_b16 v130, v145 offset:3600
	ds_write_b16 v130, v146 offset:3744
	ds_write_b16 v130, v147 offset:3888
	v_mul_f32_e32 v140, 0xbfb8aa3b, v80
	v_mul_f32_e32 v141, 0xbfb8aa3b, v81
	v_mul_f32_e32 v142, 0xbfb8aa3b, v82
	v_mul_f32_e32 v143, 0xbfb8aa3b, v83
	v_mul_f32_e32 v144, 0xbfb8aa3b, v84
	v_mul_f32_e32 v145, 0xbfb8aa3b, v85
	v_mul_f32_e32 v146, 0xbfb8aa3b, v86
	v_mul_f32_e32 v147, 0xbfb8aa3b, v87
	v_exp_f32_e32 v140, v140
	v_exp_f32_e32 v141, v141
	v_exp_f32_e32 v142, v142
	v_exp_f32_e32 v143, v143
	v_exp_f32_e32 v144, v144
	v_exp_f32_e32 v145, v145
	v_exp_f32_e32 v146, v146
	v_exp_f32_e32 v147, v147
	v_add_f32_e32 v140, 1.0, v140
	v_add_f32_e32 v141, 1.0, v141
	v_add_f32_e32 v142, 1.0, v142
	v_add_f32_e32 v143, 1.0, v143
	v_add_f32_e32 v144, 1.0, v144
	v_add_f32_e32 v145, 1.0, v145
	v_add_f32_e32 v146, 1.0, v146
	v_add_f32_e32 v147, 1.0, v147
	v_rcp_f32_e32 v140, v140
	v_rcp_f32_e32 v141, v141
	v_rcp_f32_e32 v142, v142
	v_rcp_f32_e32 v143, v143
	v_rcp_f32_e32 v144, v144
	v_rcp_f32_e32 v145, v145
	v_rcp_f32_e32 v146, v146
	v_rcp_f32_e32 v147, v147
	v_mul_f32_e32 v140, v80, v140
	v_mul_f32_e32 v141, v81, v141
	v_mul_f32_e32 v142, v82, v142
	v_mul_f32_e32 v143, v83, v143
	v_mul_f32_e32 v144, v84, v144
	v_mul_f32_e32 v145, v85, v145
	v_mul_f32_e32 v146, v86, v146
	v_mul_f32_e32 v147, v87, v147
	v_mul_f32_e32 v140, v64, v140
	v_mul_f32_e32 v141, v65, v141
	v_mul_f32_e32 v142, v66, v142
	v_mul_f32_e32 v143, v67, v143
	v_mul_f32_e32 v144, v68, v144
	v_mul_f32_e32 v145, v69, v145
	v_mul_f32_e32 v146, v70, v146
	v_mul_f32_e32 v147, v71, v147
	v_cvt_pk_bf16_f32 v140, v140, v140
	v_cvt_pk_bf16_f32 v141, v141, v141
	v_cvt_pk_bf16_f32 v142, v142, v142
	v_cvt_pk_bf16_f32 v143, v143, v143
	v_cvt_pk_bf16_f32 v144, v144, v144
	v_cvt_pk_bf16_f32 v145, v145, v145
	v_cvt_pk_bf16_f32 v146, v146, v146
	v_cvt_pk_bf16_f32 v147, v147, v147
	ds_write_b16 v130, v140 offset:4608
	ds_write_b16 v130, v141 offset:4752
	ds_write_b16 v130, v142 offset:4896
	ds_write_b16 v130, v143 offset:5040
	ds_write_b16 v130, v144 offset:5760
	ds_write_b16 v130, v145 offset:5904
	ds_write_b16 v130, v146 offset:6048
	ds_write_b16 v130, v147 offset:6192
	v_mul_f32_e32 v140, 0xbfb8aa3b, v88
	v_mul_f32_e32 v141, 0xbfb8aa3b, v89
	v_mul_f32_e32 v142, 0xbfb8aa3b, v90
	v_mul_f32_e32 v143, 0xbfb8aa3b, v91
	v_mul_f32_e32 v144, 0xbfb8aa3b, v92
	v_mul_f32_e32 v145, 0xbfb8aa3b, v93
	v_mul_f32_e32 v146, 0xbfb8aa3b, v94
	v_mul_f32_e32 v147, 0xbfb8aa3b, v95
	v_exp_f32_e32 v140, v140
	v_exp_f32_e32 v141, v141
	v_exp_f32_e32 v142, v142
	v_exp_f32_e32 v143, v143
	v_exp_f32_e32 v144, v144
	v_exp_f32_e32 v145, v145
	v_exp_f32_e32 v146, v146
	v_exp_f32_e32 v147, v147
	v_add_f32_e32 v140, 1.0, v140
	v_add_f32_e32 v141, 1.0, v141
	v_add_f32_e32 v142, 1.0, v142
	v_add_f32_e32 v143, 1.0, v143
	v_add_f32_e32 v144, 1.0, v144
	v_add_f32_e32 v145, 1.0, v145
	v_add_f32_e32 v146, 1.0, v146
	v_add_f32_e32 v147, 1.0, v147
	v_rcp_f32_e32 v140, v140
	v_rcp_f32_e32 v141, v141
	v_rcp_f32_e32 v142, v142
	v_rcp_f32_e32 v143, v143
	v_rcp_f32_e32 v144, v144
	v_rcp_f32_e32 v145, v145
	v_rcp_f32_e32 v146, v146
	v_rcp_f32_e32 v147, v147
	v_mul_f32_e32 v140, v88, v140
	v_mul_f32_e32 v141, v89, v141
	v_mul_f32_e32 v142, v90, v142
	v_mul_f32_e32 v143, v91, v143
	v_mul_f32_e32 v144, v92, v144
	v_mul_f32_e32 v145, v93, v145
	v_mul_f32_e32 v146, v94, v146
	v_mul_f32_e32 v147, v95, v147
	v_mul_f32_e32 v140, v72, v140
	v_mul_f32_e32 v141, v73, v141
	v_mul_f32_e32 v142, v74, v142
	v_mul_f32_e32 v143, v75, v143
	v_mul_f32_e32 v144, v76, v144
	v_mul_f32_e32 v145, v77, v145
	v_mul_f32_e32 v146, v78, v146
	v_mul_f32_e32 v147, v79, v147
	v_cvt_pk_bf16_f32 v140, v140, v140
	v_cvt_pk_bf16_f32 v141, v141, v141
	v_cvt_pk_bf16_f32 v142, v142, v142
	v_cvt_pk_bf16_f32 v143, v143, v143
	v_cvt_pk_bf16_f32 v144, v144, v144
	v_cvt_pk_bf16_f32 v145, v145, v145
	v_cvt_pk_bf16_f32 v146, v146, v146
	v_cvt_pk_bf16_f32 v147, v147, v147
	ds_write_b16 v130, v140 offset:6912
	ds_write_b16 v130, v141 offset:7056
	ds_write_b16 v130, v142 offset:7200
	ds_write_b16 v130, v143 offset:7344
	ds_write_b16 v130, v144 offset:8064
	ds_write_b16 v130, v145 offset:8208
	ds_write_b16 v130, v146 offset:8352
	ds_write_b16 v130, v147 offset:8496
	s_waitcnt lgkmcnt(0)
	ds_read_b128 v[148:151], v131
	ds_read_b128 v[152:155], v131 offset:2304
	ds_read_b128 v[156:159], v131 offset:4608
	ds_read_b128 v[160:163], v131 offset:6912
	s_waitcnt lgkmcnt(3)
	global_store_dwordx4 v132, v[148:151], s[12:13]
	s_waitcnt lgkmcnt(2)
	global_store_dwordx4 v132, v[152:155], s[12:13] offset:256
	s_waitcnt lgkmcnt(1)
	global_store_dwordx4 v133, v[156:159], s[12:13]
	s_waitcnt lgkmcnt(0)
	global_store_dwordx4 v133, v[160:163], s[12:13] offset:256
	v_mul_f32_e32 v140, 0xbfb8aa3b, v48
	v_mul_f32_e32 v141, 0xbfb8aa3b, v49
	v_mul_f32_e32 v142, 0xbfb8aa3b, v50
	v_mul_f32_e32 v143, 0xbfb8aa3b, v51
	v_mul_f32_e32 v144, 0xbfb8aa3b, v52
	v_mul_f32_e32 v145, 0xbfb8aa3b, v53
	v_mul_f32_e32 v146, 0xbfb8aa3b, v54
	v_mul_f32_e32 v147, 0xbfb8aa3b, v55
	v_exp_f32_e32 v140, v140
	v_exp_f32_e32 v141, v141
	v_exp_f32_e32 v142, v142
	v_exp_f32_e32 v143, v143
	v_exp_f32_e32 v144, v144
	v_exp_f32_e32 v145, v145
	v_exp_f32_e32 v146, v146
	v_exp_f32_e32 v147, v147
	v_add_f32_e32 v140, 1.0, v140
	v_add_f32_e32 v141, 1.0, v141
	v_add_f32_e32 v142, 1.0, v142
	v_add_f32_e32 v143, 1.0, v143
	v_add_f32_e32 v144, 1.0, v144
	v_add_f32_e32 v145, 1.0, v145
	v_add_f32_e32 v146, 1.0, v146
	v_add_f32_e32 v147, 1.0, v147
	v_rcp_f32_e32 v140, v140
	v_rcp_f32_e32 v141, v141
	v_rcp_f32_e32 v142, v142
	v_rcp_f32_e32 v143, v143
	v_rcp_f32_e32 v144, v144
	v_rcp_f32_e32 v145, v145
	v_rcp_f32_e32 v146, v146
	v_rcp_f32_e32 v147, v147
	v_mul_f32_e32 v140, v48, v140
	v_mul_f32_e32 v141, v49, v141
	v_mul_f32_e32 v142, v50, v142
	v_mul_f32_e32 v143, v51, v143
	v_mul_f32_e32 v144, v52, v144
	v_mul_f32_e32 v145, v53, v145
	v_mul_f32_e32 v146, v54, v146
	v_mul_f32_e32 v147, v55, v147
	v_mul_f32_e32 v140, v32, v140
	v_mul_f32_e32 v141, v33, v141
	v_mul_f32_e32 v142, v34, v142
	v_mul_f32_e32 v143, v35, v143
	v_mul_f32_e32 v144, v36, v144
	v_mul_f32_e32 v145, v37, v145
	v_mul_f32_e32 v146, v38, v146
	v_mul_f32_e32 v147, v39, v147
	v_cvt_pk_bf16_f32 v140, v140, v140
	v_cvt_pk_bf16_f32 v141, v141, v141
	v_cvt_pk_bf16_f32 v142, v142, v142
	v_cvt_pk_bf16_f32 v143, v143, v143
	v_cvt_pk_bf16_f32 v144, v144, v144
	v_cvt_pk_bf16_f32 v145, v145, v145
	v_cvt_pk_bf16_f32 v146, v146, v146
	v_cvt_pk_bf16_f32 v147, v147, v147
	ds_write_b16 v130, v140
	ds_write_b16 v130, v141 offset:144
	ds_write_b16 v130, v142 offset:288
	ds_write_b16 v130, v143 offset:432
	ds_write_b16 v130, v144 offset:1152
	ds_write_b16 v130, v145 offset:1296
	ds_write_b16 v130, v146 offset:1440
	ds_write_b16 v130, v147 offset:1584
	v_mul_f32_e32 v140, 0xbfb8aa3b, v56
	v_mul_f32_e32 v141, 0xbfb8aa3b, v57
	v_mul_f32_e32 v142, 0xbfb8aa3b, v58
	v_mul_f32_e32 v143, 0xbfb8aa3b, v59
	v_mul_f32_e32 v144, 0xbfb8aa3b, v60
	v_mul_f32_e32 v145, 0xbfb8aa3b, v61
	v_mul_f32_e32 v146, 0xbfb8aa3b, v62
	v_mul_f32_e32 v147, 0xbfb8aa3b, v63
	v_exp_f32_e32 v140, v140
	v_exp_f32_e32 v141, v141
	v_exp_f32_e32 v142, v142
	v_exp_f32_e32 v143, v143
	v_exp_f32_e32 v144, v144
	v_exp_f32_e32 v145, v145
	v_exp_f32_e32 v146, v146
	v_exp_f32_e32 v147, v147
	v_add_f32_e32 v140, 1.0, v140
	v_add_f32_e32 v141, 1.0, v141
	v_add_f32_e32 v142, 1.0, v142
	v_add_f32_e32 v143, 1.0, v143
	v_add_f32_e32 v144, 1.0, v144
	v_add_f32_e32 v145, 1.0, v145
	v_add_f32_e32 v146, 1.0, v146
	v_add_f32_e32 v147, 1.0, v147
	v_rcp_f32_e32 v140, v140
	v_rcp_f32_e32 v141, v141
	v_rcp_f32_e32 v142, v142
	v_rcp_f32_e32 v143, v143
	v_rcp_f32_e32 v144, v144
	v_rcp_f32_e32 v145, v145
	v_rcp_f32_e32 v146, v146
	v_rcp_f32_e32 v147, v147
	v_mul_f32_e32 v140, v56, v140
	v_mul_f32_e32 v141, v57, v141
	v_mul_f32_e32 v142, v58, v142
	v_mul_f32_e32 v143, v59, v143
	v_mul_f32_e32 v144, v60, v144
	v_mul_f32_e32 v145, v61, v145
	v_mul_f32_e32 v146, v62, v146
	v_mul_f32_e32 v147, v63, v147
	v_mul_f32_e32 v140, v40, v140
	v_mul_f32_e32 v141, v41, v141
	v_mul_f32_e32 v142, v42, v142
	v_mul_f32_e32 v143, v43, v143
	v_mul_f32_e32 v144, v44, v144
	v_mul_f32_e32 v145, v45, v145
	v_mul_f32_e32 v146, v46, v146
	v_mul_f32_e32 v147, v47, v147
	v_cvt_pk_bf16_f32 v140, v140, v140
	v_cvt_pk_bf16_f32 v141, v141, v141
	v_cvt_pk_bf16_f32 v142, v142, v142
	v_cvt_pk_bf16_f32 v143, v143, v143
	v_cvt_pk_bf16_f32 v144, v144, v144
	v_cvt_pk_bf16_f32 v145, v145, v145
	v_cvt_pk_bf16_f32 v146, v146, v146
	v_cvt_pk_bf16_f32 v147, v147, v147
	ds_write_b16 v130, v140 offset:2304
	ds_write_b16 v130, v141 offset:2448
	ds_write_b16 v130, v142 offset:2592
	ds_write_b16 v130, v143 offset:2736
	ds_write_b16 v130, v144 offset:3456
	ds_write_b16 v130, v145 offset:3600
	ds_write_b16 v130, v146 offset:3744
	ds_write_b16 v130, v147 offset:3888
	v_mul_f32_e32 v140, 0xbfb8aa3b, v16
	v_mul_f32_e32 v141, 0xbfb8aa3b, v17
	v_mul_f32_e32 v142, 0xbfb8aa3b, v18
	v_mul_f32_e32 v143, 0xbfb8aa3b, v19
	v_mul_f32_e32 v144, 0xbfb8aa3b, v20
	v_mul_f32_e32 v145, 0xbfb8aa3b, v21
	v_mul_f32_e32 v146, 0xbfb8aa3b, v22
	v_mul_f32_e32 v147, 0xbfb8aa3b, v23
	v_exp_f32_e32 v140, v140
	v_exp_f32_e32 v141, v141
	v_exp_f32_e32 v142, v142
	v_exp_f32_e32 v143, v143
	v_exp_f32_e32 v144, v144
	v_exp_f32_e32 v145, v145
	v_exp_f32_e32 v146, v146
	v_exp_f32_e32 v147, v147
	v_add_f32_e32 v140, 1.0, v140
	v_add_f32_e32 v141, 1.0, v141
	v_add_f32_e32 v142, 1.0, v142
	v_add_f32_e32 v143, 1.0, v143
	v_add_f32_e32 v144, 1.0, v144
	v_add_f32_e32 v145, 1.0, v145
	v_add_f32_e32 v146, 1.0, v146
	v_add_f32_e32 v147, 1.0, v147
	v_rcp_f32_e32 v140, v140
	v_rcp_f32_e32 v141, v141
	v_rcp_f32_e32 v142, v142
	v_rcp_f32_e32 v143, v143
	v_rcp_f32_e32 v144, v144
	v_rcp_f32_e32 v145, v145
	v_rcp_f32_e32 v146, v146
	v_rcp_f32_e32 v147, v147
	v_mul_f32_e32 v140, v16, v140
	v_mul_f32_e32 v141, v17, v141
	v_mul_f32_e32 v142, v18, v142
	v_mul_f32_e32 v143, v19, v143
	v_mul_f32_e32 v144, v20, v144
	v_mul_f32_e32 v145, v21, v145
	v_mul_f32_e32 v146, v22, v146
	v_mul_f32_e32 v147, v23, v147
	v_mul_f32_e32 v140, v0, v140
	v_mul_f32_e32 v141, v1, v141
	v_mul_f32_e32 v142, v2, v142
	v_mul_f32_e32 v143, v3, v143
	v_mul_f32_e32 v144, v4, v144
	v_mul_f32_e32 v145, v5, v145
	v_mul_f32_e32 v146, v6, v146
	v_mul_f32_e32 v147, v7, v147
	v_cvt_pk_bf16_f32 v140, v140, v140
	v_cvt_pk_bf16_f32 v141, v141, v141
	v_cvt_pk_bf16_f32 v142, v142, v142
	v_cvt_pk_bf16_f32 v143, v143, v143
	v_cvt_pk_bf16_f32 v144, v144, v144
	v_cvt_pk_bf16_f32 v145, v145, v145
	v_cvt_pk_bf16_f32 v146, v146, v146
	v_cvt_pk_bf16_f32 v147, v147, v147
	ds_write_b16 v130, v140 offset:4608
	ds_write_b16 v130, v141 offset:4752
	ds_write_b16 v130, v142 offset:4896
	ds_write_b16 v130, v143 offset:5040
	ds_write_b16 v130, v144 offset:5760
	ds_write_b16 v130, v145 offset:5904
	ds_write_b16 v130, v146 offset:6048
	ds_write_b16 v130, v147 offset:6192
	v_mul_f32_e32 v140, 0xbfb8aa3b, v24
	v_mul_f32_e32 v141, 0xbfb8aa3b, v25
	v_mul_f32_e32 v142, 0xbfb8aa3b, v26
	v_mul_f32_e32 v143, 0xbfb8aa3b, v27
	v_mul_f32_e32 v144, 0xbfb8aa3b, v28
	v_mul_f32_e32 v145, 0xbfb8aa3b, v29
	v_mul_f32_e32 v146, 0xbfb8aa3b, v30
	v_mul_f32_e32 v147, 0xbfb8aa3b, v31
	v_exp_f32_e32 v140, v140
	v_exp_f32_e32 v141, v141
	v_exp_f32_e32 v142, v142
	v_exp_f32_e32 v143, v143
	v_exp_f32_e32 v144, v144
	v_exp_f32_e32 v145, v145
	v_exp_f32_e32 v146, v146
	v_exp_f32_e32 v147, v147
	v_add_f32_e32 v140, 1.0, v140
	v_add_f32_e32 v141, 1.0, v141
	v_add_f32_e32 v142, 1.0, v142
	v_add_f32_e32 v143, 1.0, v143
	v_add_f32_e32 v144, 1.0, v144
	v_add_f32_e32 v145, 1.0, v145
	v_add_f32_e32 v146, 1.0, v146
	v_add_f32_e32 v147, 1.0, v147
	v_rcp_f32_e32 v140, v140
	v_rcp_f32_e32 v141, v141
	v_rcp_f32_e32 v142, v142
	v_rcp_f32_e32 v143, v143
	v_rcp_f32_e32 v144, v144
	v_rcp_f32_e32 v145, v145
	v_rcp_f32_e32 v146, v146
	v_rcp_f32_e32 v147, v147
	v_mul_f32_e32 v140, v24, v140
	v_mul_f32_e32 v141, v25, v141
	v_mul_f32_e32 v142, v26, v142
	v_mul_f32_e32 v143, v27, v143
	v_mul_f32_e32 v144, v28, v144
	v_mul_f32_e32 v145, v29, v145
	v_mul_f32_e32 v146, v30, v146
	v_mul_f32_e32 v147, v31, v147
	v_mul_f32_e32 v140, v8, v140
	v_mul_f32_e32 v141, v9, v141
	v_mul_f32_e32 v142, v10, v142
	v_mul_f32_e32 v143, v11, v143
	v_mul_f32_e32 v144, v12, v144
	v_mul_f32_e32 v145, v13, v145
	v_mul_f32_e32 v146, v14, v146
	v_mul_f32_e32 v147, v15, v147
	v_cvt_pk_bf16_f32 v140, v140, v140
	v_cvt_pk_bf16_f32 v141, v141, v141
	v_cvt_pk_bf16_f32 v142, v142, v142
	v_cvt_pk_bf16_f32 v143, v143, v143
	v_cvt_pk_bf16_f32 v144, v144, v144
	v_cvt_pk_bf16_f32 v145, v145, v145
	v_cvt_pk_bf16_f32 v146, v146, v146
	v_cvt_pk_bf16_f32 v147, v147, v147
	ds_write_b16 v130, v140 offset:6912
	ds_write_b16 v130, v141 offset:7056
	ds_write_b16 v130, v142 offset:7200
	ds_write_b16 v130, v143 offset:7344
	ds_write_b16 v130, v144 offset:8064
	ds_write_b16 v130, v145 offset:8208
	ds_write_b16 v130, v146 offset:8352
	ds_write_b16 v130, v147 offset:8496
	s_waitcnt lgkmcnt(0)
	ds_read_b128 v[148:151], v131
	ds_read_b128 v[152:155], v131 offset:2304
	ds_read_b128 v[156:159], v131 offset:4608
	ds_read_b128 v[160:163], v131 offset:6912
	s_waitcnt lgkmcnt(3)
	global_store_dwordx4 v132, v[148:151], s[12:13] offset:2048
	s_waitcnt lgkmcnt(2)
	global_store_dwordx4 v132, v[152:155], s[12:13] offset:2304
	s_waitcnt lgkmcnt(1)
	global_store_dwordx4 v133, v[156:159], s[12:13] offset:2048
	s_waitcnt lgkmcnt(0)
	global_store_dwordx4 v133, v[160:163], s[12:13] offset:2304
	v_readlane_b32 s0, v254, 11
	s_add_i32 s2, s2, s0
	s_cmp_lt_i32 s2, s3
	s_barrier
	s_cbranch_scc1 .LBB0_1031
